# static odd-slot s_setprio 1 at phase start removed (all waves start each phase at priority 0): A/B of the asymmetric priority in the attention phases
# speedup vs baseline: 1.0011x; 1.0011x over previous
.LBB0_9:
	s_setprio 0
	s_mov_b64 s[22:23], 0
	v_readlane_b32 s0, v249, 8
	s_lshl_b64 s[20:21], s[22:23], 2
	v_readlane_b32 s2, v249, 10
	v_readlane_b32 s1, v249, 9
	v_readlane_b32 s3, v249, 11
	s_add_u32 s0, s2, s20
	s_addc_u32 s1, s3, s21
	v_writelane_b32 v252, s0, 31
	s_nop 1
	v_writelane_b32 v252, s1, 32
	v_readlane_b32 s0, v249, 6
	v_readlane_b32 s1, v249, 7
	s_cmp_lg_u32 s0, 28
	s_mov_b64 s[0:1], -1
	s_cbranch_scc1 .LBB0_10
	s_getpc_b64 s[98:99]
